# gate_up GEMM SwiGLU epilogue de-serialised: 8 per-row rowss loads hoisted and waited once, per-row vmcnt(0) ladder removed
# speedup vs baseline: 1.0066x; 1.0031x over previous
; __device__ __forceinline__ unsigned pk2(float lo, float hi) { unsigned r; asm volatile("v_cvt_pk_bf16_f32 %0, %1, %2" : "=v"(r) : "v"(lo), "v"(hi)); return r; }
; __device__ __forceinline__ float sigmoidf_(float x) { return frcp(1.0f + fexp2(-x * LOG2E)); }
;     __device__ __forceinline__ void operator()(const f32x4 (&acc)[2][2][4][2], const Unit& u, int wr, int wc, int fr, int fq) const {
;         const int row0 = u.pm * BM + wr * 64 + fr, col0 = u.pn * HALF + wc * 32 + 8 * fq; const float* cb = c2 + (size_t)(u.pm >> 4) * (2 * DFF) + col0;
;         const f32x4 cg[2] = {*(const f32x4*)cb, *(const f32x4*)(cb + 4)}, cu[2] = {*(const f32x4*)(cb + DFF), *(const f32x4*)(cb + DFF + 4)};
; #pragma unroll
;         for (int ai = 0; ai < 2; ++ai)
; #pragma unroll
;             for (int m = 0; m < 4; ++m) { bf16_t* rowp = O + (size_t)(row0 + ai * HALF + m * 16) * DFF + col0; float v[8];
;                 const float rs = __builtin_amdgcn_rsqf(rowss[row0 + ai * HALF + m * 16] * (1.0f / DM) + 1e-6f);
; #pragma unroll
;                 for (int n = 0; n < 2; ++n)
; #pragma unroll
;                     for (int j = 0; j < 4; ++j) { const float g = __builtin_fmaf(rs, acc[ai][0][m][n][j], cg[n][j]), up = __builtin_fmaf(rs, acc[ai][1][m][n][j], cu[n][j]); v[4 * n + j] = g * sigmoidf_(g) * up; }
;                 u32x4 w; w.x = pk2(v[0], v[1]); w.y = pk2(v[2], v[3]); w.z = pk2(v[4], v[5]); w.w = pk2(v[6], v[7]);
;                 *(u32x4*)rowp = w; }
.LBB0_1058:
	s_ashr_i32 s15, s22, 4
	s_mul_hi_i32 s17, s15, 0xb000
	s_mul_i32 s15, s15, 0xb000
	v_lshl_add_u32 v162, s22, 8, v153
	v_lshl_or_b32 v168, s33, 7, v170
	s_add_u32 s24, s84, s15
	s_addc_u32 s25, s85, s17
	v_ashrrev_i32_e32 v169, 31, v168
	v_ashrrev_i32_e32 v163, 31, v162
	v_lshl_add_u64 v[88:89], v[168:169], 2, s[24:25]
	v_lshl_add_u64 v[166:167], v[162:163], 2, s[0:1]
	global_load_dwordx4 v[80:83], v[88:89], off
	global_load_dword v163, v[166:167], off
	global_load_dword v190, v[166:167], off offset:64
	global_load_dword v191, v[166:167], off offset:128
	global_load_dword v192, v[166:167], off offset:192
	global_load_dword v193, v[166:167], off offset:512
	global_load_dword v194, v[166:167], off offset:576
	global_load_dword v195, v[166:167], off offset:640
	global_load_dword v196, v[166:167], off offset:704
	v_add_co_u32_e32 v90, vcc, s45, v88
	v_or_b32_e32 v180, 16, v162
	s_nop 0
	v_addc_co_u32_e32 v91, vcc, 0, v89, vcc
	global_load_dwordx4 v[92:95], v[90:91], off offset:2048
	global_load_dwordx4 v[96:99], v[88:89], off offset:16
	v_lshl_add_u64 v[88:89], v[88:89], 0, s[12:13]
	global_load_dwordx4 v[88:91], v[88:89], off offset:16
	v_ashrrev_i32_e32 v181, 31, v180
	v_lshl_add_u64 v[182:183], v[180:181], 2, s[0:1]
	v_mov_b64_e32 v[164:165], s[76:77]
	v_mad_i64_i32 v[178:179], s[24:25], v162, s46, v[164:165]
	v_lshlrev_b64 v[168:169], 1, v[168:169]
	v_lshl_add_u64 v[178:179], v[178:179], 0, v[168:169]
	s_andn2_b64 vcc, exec, s[2:3]
	s_mov_b64 s[2:3], -1
	s_waitcnt vmcnt(0)
	v_fmamk_f32 v163, v163, 0x3a000000, v174
	v_rsq_f32_e32 v163, v163
	s_nop 0
	v_fma_f32 v140, v163, v140, v80
	v_fma_f32 v139, v163, v139, v99
	v_fma_f32 v141, v163, v141, v81
	v_fma_f32 v142, v163, v142, v82
	v_fma_f32 v143, v163, v143, v83
	v_fma_f32 v136, v163, v136, v96
	v_fma_f32 v137, v163, v137, v97
	v_fma_f32 v138, v163, v138, v98
	v_mul_f32_e32 v188, 0xbfb8aa3b, v139
	v_fma_f32 v132, v163, v132, v92
	v_fma_f32 v133, v163, v133, v93
	v_fma_f32 v134, v163, v134, v94
	v_fma_f32 v135, v163, v135, v95
	v_fma_f32 v128, v163, v128, v88
	v_fma_f32 v129, v163, v129, v89
	v_fma_f32 v130, v163, v130, v90
	v_fma_f32 v131, v163, v131, v91
	v_mul_f32_e32 v163, 0xbfb8aa3b, v140
	v_mul_f32_e32 v177, 0xbfb8aa3b, v141
	v_mul_f32_e32 v181, 0xbfb8aa3b, v142
	v_mul_f32_e32 v184, 0xbfb8aa3b, v143
	v_mul_f32_e32 v185, 0xbfb8aa3b, v136
	v_mul_f32_e32 v186, 0xbfb8aa3b, v137
	v_mul_f32_e32 v187, 0xbfb8aa3b, v138
	v_exp_f32_e32 v188, v188
	v_exp_f32_e32 v163, v163
	v_exp_f32_e32 v177, v177
	v_exp_f32_e32 v181, v181
	v_exp_f32_e32 v184, v184
	v_exp_f32_e32 v185, v185
	v_exp_f32_e32 v186, v186
	v_exp_f32_e32 v187, v187
	v_add_f32_e32 v188, 1.0, v188
	v_add_f32_e32 v163, 1.0, v163
	v_add_f32_e32 v177, 1.0, v177
	v_add_f32_e32 v181, 1.0, v181
	v_add_f32_e32 v184, 1.0, v184
	v_add_f32_e32 v185, 1.0, v185
	v_add_f32_e32 v186, 1.0, v186
	v_add_f32_e32 v187, 1.0, v187
	v_rcp_f32_e32 v188, v188
	v_rcp_f32_e32 v163, v163
	v_rcp_f32_e32 v177, v177
	v_rcp_f32_e32 v181, v181
	v_rcp_f32_e32 v184, v184
	v_rcp_f32_e32 v185, v185
	v_rcp_f32_e32 v186, v186
	v_rcp_f32_e32 v187, v187
	v_mul_f32_e32 v139, v139, v188
	v_mul_f32_e32 v140, v140, v163
	v_mul_f32_e32 v141, v141, v177
	v_mul_f32_e32 v142, v142, v181
	v_mul_f32_e32 v143, v143, v184
	v_mul_f32_e32 v136, v136, v185
	v_mul_f32_e32 v137, v137, v186
	v_mul_f32_e32 v138, v138, v187
	v_mul_f32_e32 v131, v131, v139
	v_mul_f32_e32 v132, v132, v140
	v_mul_f32_e32 v133, v133, v141
	v_mul_f32_e32 v134, v134, v142
	v_mul_f32_e32 v135, v135, v143
	v_mul_f32_e32 v136, v128, v136
	v_mul_f32_e32 v137, v129, v137
	v_mul_f32_e32 v138, v130, v138
	v_cvt_pk_bf16_f32 v128, v132, v133
	v_cvt_pk_bf16_f32 v129, v134, v135
	v_cvt_pk_bf16_f32 v130, v136, v137
	v_cvt_pk_bf16_f32 v131, v138, v131
	global_store_dwordx4 v[178:179], v[128:131], off
	s_nop 0
	s_nop 0
	v_or_b32_e32 v128, 32, v162
	v_mad_i64_i32 v[130:131], s[24:25], v180, s46, v[164:165]
	v_lshl_add_u64 v[130:131], v[130:131], 0, v[168:169]
	s_nop 0
	v_fmamk_f32 v129, v190, 0x3a000000, v174
	v_rsq_f32_e32 v134, v129
	v_ashrrev_i32_e32 v129, 31, v128
	v_lshl_add_u64 v[132:133], v[128:129], 2, s[0:1]
	v_fma_f32 v123, v134, v123, v99
	v_fma_f32 v124, v134, v124, v80
	v_fma_f32 v125, v134, v125, v81
	v_fma_f32 v126, v134, v126, v82
	v_fma_f32 v127, v134, v127, v83
	v_fma_f32 v120, v134, v120, v96
	v_fma_f32 v121, v134, v121, v97
	v_fma_f32 v122, v134, v122, v98
	v_mul_f32_e32 v140, 0xbfb8aa3b, v123
	v_fma_f32 v116, v134, v116, v92
	v_fma_f32 v117, v134, v117, v93
	v_fma_f32 v118, v134, v118, v94
	v_fma_f32 v119, v134, v119, v95
	v_fma_f32 v112, v134, v112, v88
	v_fma_f32 v113, v134, v113, v89
	v_fma_f32 v114, v134, v114, v90
	v_fma_f32 v115, v134, v115, v91
	v_mul_f32_e32 v129, 0xbfb8aa3b, v124
	v_mul_f32_e32 v134, 0xbfb8aa3b, v125
	v_mul_f32_e32 v135, 0xbfb8aa3b, v126
	v_mul_f32_e32 v136, 0xbfb8aa3b, v127
	v_mul_f32_e32 v137, 0xbfb8aa3b, v120
	v_mul_f32_e32 v138, 0xbfb8aa3b, v121
	v_mul_f32_e32 v139, 0xbfb8aa3b, v122
	v_exp_f32_e32 v140, v140
	v_exp_f32_e32 v129, v129
	v_exp_f32_e32 v134, v134
	v_exp_f32_e32 v135, v135
	v_exp_f32_e32 v136, v136
	v_exp_f32_e32 v137, v137
	v_exp_f32_e32 v138, v138
	v_exp_f32_e32 v139, v139
	v_add_f32_e32 v140, 1.0, v140
	v_add_f32_e32 v129, 1.0, v129
	v_add_f32_e32 v134, 1.0, v134
	v_add_f32_e32 v135, 1.0, v135
	v_add_f32_e32 v136, 1.0, v136
	v_add_f32_e32 v137, 1.0, v137
	v_add_f32_e32 v138, 1.0, v138
	v_add_f32_e32 v139, 1.0, v139
	v_rcp_f32_e32 v140, v140
	v_rcp_f32_e32 v129, v129
	v_rcp_f32_e32 v134, v134
	v_rcp_f32_e32 v135, v135
	v_rcp_f32_e32 v136, v136
	v_rcp_f32_e32 v137, v137
	v_rcp_f32_e32 v138, v138
	v_rcp_f32_e32 v139, v139
	v_mul_f32_e32 v123, v123, v140
; __device__ __forceinline__ unsigned pk2(float lo, float hi) { unsigned r; asm volatile("v_cvt_pk_bf16_f32 %0, %1, %2" : "=v"(r) : "v"(lo), "v"(hi)); return r; }
; __device__ __forceinline__ float sigmoidf_(float x) { return frcp(1.0f + fexp2(-x * LOG2E)); }
;     __device__ __forceinline__ void operator()(const f32x4 (&acc)[2][2][4][2], const Unit& u, int wr, int wc, int fr, int fq) const {
;         const int row0 = u.pm * BM + wr * 64 + fr, col0 = u.pn * HALF + wc * 32 + 8 * fq; const float* cb = c2 + (size_t)(u.pm >> 4) * (2 * DFF) + col0;
;         const f32x4 cg[2] = {*(const f32x4*)cb, *(const f32x4*)(cb + 4)}, cu[2] = {*(const f32x4*)(cb + DFF), *(const f32x4*)(cb + DFF + 4)};
; #pragma unroll
;         for (int ai = 0; ai < 2; ++ai)
; #pragma unroll
;             for (int m = 0; m < 4; ++m) { bf16_t* rowp = O + (size_t)(row0 + ai * HALF + m * 16) * DFF + col0; float v[8];
;                 const float rs = __builtin_amdgcn_rsqf(rowss[row0 + ai * HALF + m * 16] * (1.0f / DM) + 1e-6f);
; #pragma unroll
;                 for (int n = 0; n < 2; ++n)
; #pragma unroll
;                     for (int j = 0; j < 4; ++j) { const float g = __builtin_fmaf(rs, acc[ai][0][m][n][j], cg[n][j]), up = __builtin_fmaf(rs, acc[ai][1][m][n][j], cu[n][j]); v[4 * n + j] = g * sigmoidf_(g) * up; }
;                 u32x4 w; w.x = pk2(v[0], v[1]); w.y = pk2(v[2], v[3]); w.z = pk2(v[4], v[5]); w.w = pk2(v[6], v[7]);
;                 *(u32x4*)rowp = w; }
	v_mul_f32_e32 v124, v124, v129
	v_mul_f32_e32 v125, v125, v134
	v_mul_f32_e32 v126, v126, v135
	v_mul_f32_e32 v127, v127, v136
	v_mul_f32_e32 v120, v120, v137
	v_mul_f32_e32 v121, v121, v138
	v_mul_f32_e32 v122, v122, v139
	v_mul_f32_e32 v115, v115, v123
	v_mul_f32_e32 v116, v116, v124
	v_mul_f32_e32 v117, v117, v125
	v_mul_f32_e32 v118, v118, v126
	v_mul_f32_e32 v119, v119, v127
	v_mul_f32_e32 v120, v112, v120
	v_mul_f32_e32 v121, v113, v121
	v_mul_f32_e32 v122, v114, v122
	v_cvt_pk_bf16_f32 v112, v116, v117
	v_cvt_pk_bf16_f32 v113, v118, v119
	v_cvt_pk_bf16_f32 v114, v120, v121
	v_cvt_pk_bf16_f32 v115, v122, v115
	global_store_dwordx4 v[130:131], v[112:115], off
	s_nop 0
	s_nop 0
	v_or_b32_e32 v112, 48, v162
	v_mad_i64_i32 v[114:115], s[24:25], v128, s46, v[164:165]
	v_lshl_add_u64 v[114:115], v[114:115], 0, v[168:169]
	s_nop 0
	v_fmamk_f32 v113, v191, 0x3a000000, v174
	v_rsq_f32_e32 v118, v113
	v_ashrrev_i32_e32 v113, 31, v112
	v_lshl_add_u64 v[116:117], v[112:113], 2, s[0:1]
	v_fma_f32 v107, v118, v107, v99
	v_fma_f32 v108, v118, v108, v80
	v_fma_f32 v109, v118, v109, v81
	v_fma_f32 v110, v118, v110, v82
	v_fma_f32 v111, v118, v111, v83
	v_fma_f32 v104, v118, v104, v96
	v_fma_f32 v105, v118, v105, v97
	v_fma_f32 v106, v118, v106, v98
	v_mul_f32_e32 v124, 0xbfb8aa3b, v107
	v_fma_f32 v100, v118, v100, v92
	v_fma_f32 v101, v118, v101, v93
	v_fma_f32 v102, v118, v102, v94
	v_fma_f32 v103, v118, v103, v95
	v_fma_f32 v84, v118, v84, v88
	v_fma_f32 v85, v118, v85, v89
	v_fma_f32 v86, v118, v86, v90
	v_fma_f32 v87, v118, v87, v91
	v_mul_f32_e32 v113, 0xbfb8aa3b, v108
	v_mul_f32_e32 v118, 0xbfb8aa3b, v109
	v_mul_f32_e32 v119, 0xbfb8aa3b, v110
	v_mul_f32_e32 v120, 0xbfb8aa3b, v111
	v_mul_f32_e32 v121, 0xbfb8aa3b, v104
	v_mul_f32_e32 v122, 0xbfb8aa3b, v105
	v_mul_f32_e32 v123, 0xbfb8aa3b, v106
	v_exp_f32_e32 v124, v124
	v_exp_f32_e32 v113, v113
	v_exp_f32_e32 v118, v118
	v_exp_f32_e32 v119, v119
	v_exp_f32_e32 v120, v120
	v_exp_f32_e32 v121, v121
	v_exp_f32_e32 v122, v122
	v_exp_f32_e32 v123, v123
	v_add_f32_e32 v124, 1.0, v124
	v_add_f32_e32 v113, 1.0, v113
	v_add_f32_e32 v118, 1.0, v118
	v_add_f32_e32 v119, 1.0, v119
	v_add_f32_e32 v120, 1.0, v120
	v_add_f32_e32 v121, 1.0, v121
	v_add_f32_e32 v122, 1.0, v122
	v_add_f32_e32 v123, 1.0, v123
	v_rcp_f32_e32 v124, v124
	v_rcp_f32_e32 v113, v113
	v_rcp_f32_e32 v118, v118
	v_rcp_f32_e32 v119, v119
	v_rcp_f32_e32 v120, v120
	v_rcp_f32_e32 v121, v121
	v_rcp_f32_e32 v122, v122
	v_rcp_f32_e32 v123, v123
	v_mul_f32_e32 v107, v107, v124
	v_mul_f32_e32 v108, v108, v113
	v_mul_f32_e32 v109, v109, v118
	v_mul_f32_e32 v110, v110, v119
	v_mul_f32_e32 v111, v111, v120
	v_mul_f32_e32 v104, v104, v121
	v_mul_f32_e32 v105, v105, v122
	v_mul_f32_e32 v106, v106, v123
	v_mul_f32_e32 v87, v87, v107
	v_mul_f32_e32 v100, v100, v108
	v_mul_f32_e32 v101, v101, v109
	v_mul_f32_e32 v102, v102, v110
	v_mul_f32_e32 v103, v103, v111
	v_mul_f32_e32 v104, v84, v104
	v_mul_f32_e32 v105, v85, v105
	v_mul_f32_e32 v106, v86, v106
	v_cvt_pk_bf16_f32 v84, v100, v101
	v_cvt_pk_bf16_f32 v85, v102, v103
	v_cvt_pk_bf16_f32 v86, v104, v105
	v_cvt_pk_bf16_f32 v87, v106, v87
	global_store_dwordx4 v[114:115], v[84:87], off
	s_nop 0
	s_nop 0
	v_fmamk_f32 v84, v192, 0x3a000000, v174
	v_rsq_f32_e32 v86, v84
	v_mad_i64_i32 v[84:85], s[24:25], v112, s46, v[164:165]
	v_lshl_add_u64 v[84:85], v[84:85], 0, v[168:169]
	v_fma_f32 v75, v86, v75, v99
	v_fma_f32 v76, v86, v76, v80
	v_fma_f32 v77, v86, v77, v81
	v_fma_f32 v78, v86, v78, v82
	v_fma_f32 v79, v86, v79, v83
	v_fma_f32 v72, v86, v72, v96
	v_fma_f32 v73, v86, v73, v97
	v_fma_f32 v74, v86, v74, v98
	v_mul_f32_e32 v105, 0xbfb8aa3b, v75
	v_fma_f32 v68, v86, v68, v92
	v_fma_f32 v69, v86, v69, v93
	v_fma_f32 v70, v86, v70, v94
	v_fma_f32 v71, v86, v71, v95
	v_fma_f32 v64, v86, v64, v88
	v_fma_f32 v65, v86, v65, v89
	v_fma_f32 v66, v86, v66, v90
	v_fma_f32 v67, v86, v67, v91
	v_mul_f32_e32 v86, 0xbfb8aa3b, v76
	v_mul_f32_e32 v87, 0xbfb8aa3b, v77
	v_mul_f32_e32 v100, 0xbfb8aa3b, v78
	v_mul_f32_e32 v101, 0xbfb8aa3b, v79
	v_mul_f32_e32 v102, 0xbfb8aa3b, v72
	v_mul_f32_e32 v103, 0xbfb8aa3b, v73
	v_mul_f32_e32 v104, 0xbfb8aa3b, v74
	v_exp_f32_e32 v105, v105
	v_exp_f32_e32 v86, v86
	v_exp_f32_e32 v87, v87
	v_exp_f32_e32 v100, v100
	v_exp_f32_e32 v101, v101
	v_exp_f32_e32 v102, v102
	v_exp_f32_e32 v103, v103
	v_exp_f32_e32 v104, v104
	v_add_f32_e32 v105, 1.0, v105
	v_add_f32_e32 v86, 1.0, v86
	v_add_f32_e32 v87, 1.0, v87
	v_add_f32_e32 v100, 1.0, v100
	v_add_f32_e32 v101, 1.0, v101
	v_add_f32_e32 v102, 1.0, v102
	v_add_f32_e32 v103, 1.0, v103
	v_add_f32_e32 v104, 1.0, v104
	v_rcp_f32_e32 v105, v105
	v_rcp_f32_e32 v86, v86
	v_rcp_f32_e32 v87, v87
	v_rcp_f32_e32 v100, v100
	v_rcp_f32_e32 v101, v101
	v_rcp_f32_e32 v102, v102
	v_rcp_f32_e32 v103, v103
	v_rcp_f32_e32 v104, v104
	v_mul_f32_e32 v75, v75, v105
	v_mul_f32_e32 v76, v76, v86
	v_mul_f32_e32 v77, v77, v87
	v_mul_f32_e32 v78, v78, v100
	v_mul_f32_e32 v79, v79, v101
	v_mul_f32_e32 v72, v72, v102
	v_mul_f32_e32 v73, v73, v103
	v_mul_f32_e32 v74, v74, v104
	v_mul_f32_e32 v67, v67, v75
	v_mul_f32_e32 v68, v68, v76
	v_mul_f32_e32 v69, v69, v77
	v_mul_f32_e32 v70, v70, v78
	v_mul_f32_e32 v71, v71, v79
	v_mul_f32_e32 v72, v64, v72
	v_mul_f32_e32 v73, v65, v73
	v_mul_f32_e32 v74, v66, v74
	v_cvt_pk_bf16_f32 v64, v68, v69
	v_cvt_pk_bf16_f32 v65, v70, v71
	v_cvt_pk_bf16_f32 v66, v72, v73
	v_cvt_pk_bf16_f32 v67, v74, v67
	global_store_dwordx4 v[84:85], v[64:67], off
	s_nop 0
	s_nop 0
	v_add_u32_e32 v65, 0x80, v162
	s_nop 0
	v_fmamk_f32 v64, v193, 0x3a000000, v174
	v_rsq_f32_e32 v66, v64
	v_mad_i64_i32 v[64:65], s[24:25], v65, s46, v[164:165]
; __device__ __forceinline__ unsigned pk2(float lo, float hi) { unsigned r; asm volatile("v_cvt_pk_bf16_f32 %0, %1, %2" : "=v"(r) : "v"(lo), "v"(hi)); return r; }
; __device__ __forceinline__ float sigmoidf_(float x) { return frcp(1.0f + fexp2(-x * LOG2E)); }
;     __device__ __forceinline__ void operator()(const f32x4 (&acc)[2][2][4][2], const Unit& u, int wr, int wc, int fr, int fq) const {
;         const int row0 = u.pm * BM + wr * 64 + fr, col0 = u.pn * HALF + wc * 32 + 8 * fq; const float* cb = c2 + (size_t)(u.pm >> 4) * (2 * DFF) + col0;
;         const f32x4 cg[2] = {*(const f32x4*)cb, *(const f32x4*)(cb + 4)}, cu[2] = {*(const f32x4*)(cb + DFF), *(const f32x4*)(cb + DFF + 4)};
; #pragma unroll
;         for (int ai = 0; ai < 2; ++ai)
; #pragma unroll
;             for (int m = 0; m < 4; ++m) { bf16_t* rowp = O + (size_t)(row0 + ai * HALF + m * 16) * DFF + col0; float v[8];
;                 const float rs = __builtin_amdgcn_rsqf(rowss[row0 + ai * HALF + m * 16] * (1.0f / DM) + 1e-6f);
; #pragma unroll
;                 for (int n = 0; n < 2; ++n)
; #pragma unroll
;                     for (int j = 0; j < 4; ++j) { const float g = __builtin_fmaf(rs, acc[ai][0][m][n][j], cg[n][j]), up = __builtin_fmaf(rs, acc[ai][1][m][n][j], cu[n][j]); v[4 * n + j] = g * sigmoidf_(g) * up; }
;                 u32x4 w; w.x = pk2(v[0], v[1]); w.y = pk2(v[2], v[3]); w.z = pk2(v[4], v[5]); w.w = pk2(v[6], v[7]);
;                 *(u32x4*)rowp = w; }
	v_lshl_add_u64 v[64:65], v[64:65], 0, v[168:169]
	v_fma_f32 v59, v66, v59, v99
	v_fma_f32 v60, v66, v60, v80
	v_fma_f32 v61, v66, v61, v81
	v_fma_f32 v62, v66, v62, v82
	v_fma_f32 v63, v66, v63, v83
	v_fma_f32 v56, v66, v56, v96
	v_fma_f32 v57, v66, v57, v97
	v_fma_f32 v58, v66, v58, v98
	v_mul_f32_e32 v73, 0xbfb8aa3b, v59
	v_fma_f32 v52, v66, v52, v92
	v_fma_f32 v53, v66, v53, v93
	v_fma_f32 v54, v66, v54, v94
	v_fma_f32 v55, v66, v55, v95
	v_fma_f32 v48, v66, v48, v88
	v_fma_f32 v49, v66, v49, v89
	v_fma_f32 v50, v66, v50, v90
	v_fma_f32 v51, v66, v51, v91
	v_mul_f32_e32 v66, 0xbfb8aa3b, v60
	v_mul_f32_e32 v67, 0xbfb8aa3b, v61
	v_mul_f32_e32 v68, 0xbfb8aa3b, v62
	v_mul_f32_e32 v69, 0xbfb8aa3b, v63
	v_mul_f32_e32 v70, 0xbfb8aa3b, v56
	v_mul_f32_e32 v71, 0xbfb8aa3b, v57
	v_mul_f32_e32 v72, 0xbfb8aa3b, v58
	v_exp_f32_e32 v73, v73
	v_exp_f32_e32 v66, v66
	v_exp_f32_e32 v67, v67
	v_exp_f32_e32 v68, v68
	v_exp_f32_e32 v69, v69
	v_exp_f32_e32 v70, v70
	v_exp_f32_e32 v71, v71
	v_exp_f32_e32 v72, v72
	v_add_f32_e32 v73, 1.0, v73
	v_add_f32_e32 v66, 1.0, v66
	v_add_f32_e32 v67, 1.0, v67
	v_add_f32_e32 v68, 1.0, v68
	v_add_f32_e32 v69, 1.0, v69
	v_add_f32_e32 v70, 1.0, v70
	v_add_f32_e32 v71, 1.0, v71
	v_add_f32_e32 v72, 1.0, v72
	v_rcp_f32_e32 v73, v73
	v_rcp_f32_e32 v66, v66
	v_rcp_f32_e32 v67, v67
	v_rcp_f32_e32 v68, v68
	v_rcp_f32_e32 v69, v69
	v_rcp_f32_e32 v70, v70
	v_rcp_f32_e32 v71, v71
	v_rcp_f32_e32 v72, v72
	v_mul_f32_e32 v59, v59, v73
	v_mul_f32_e32 v60, v60, v66
	v_mul_f32_e32 v61, v61, v67
	v_mul_f32_e32 v62, v62, v68
	v_mul_f32_e32 v63, v63, v69
	v_mul_f32_e32 v56, v56, v70
	v_mul_f32_e32 v57, v57, v71
	v_mul_f32_e32 v58, v58, v72
	v_mul_f32_e32 v51, v51, v59
	v_mul_f32_e32 v52, v52, v60
	v_mul_f32_e32 v53, v53, v61
	v_mul_f32_e32 v54, v54, v62
	v_mul_f32_e32 v55, v55, v63
	v_mul_f32_e32 v56, v48, v56
	v_mul_f32_e32 v57, v49, v57
	v_mul_f32_e32 v58, v50, v58
	v_cvt_pk_bf16_f32 v48, v52, v53
	v_cvt_pk_bf16_f32 v49, v54, v55
	v_cvt_pk_bf16_f32 v50, v56, v57
	v_cvt_pk_bf16_f32 v51, v58, v51
	global_store_dwordx4 v[64:65], v[48:51], off
	s_nop 0
	s_nop 0
	v_add_u32_e32 v49, 0x90, v162
	s_nop 0
	v_fmamk_f32 v48, v194, 0x3a000000, v174
	v_rsq_f32_e32 v50, v48
	v_mad_i64_i32 v[48:49], s[24:25], v49, s46, v[164:165]
	v_lshl_add_u64 v[48:49], v[48:49], 0, v[168:169]
	v_fma_f32 v43, v50, v43, v99
	v_fma_f32 v44, v50, v44, v80
	v_fma_f32 v45, v50, v45, v81
	v_fma_f32 v46, v50, v46, v82
	v_fma_f32 v47, v50, v47, v83
	v_fma_f32 v40, v50, v40, v96
	v_fma_f32 v41, v50, v41, v97
	v_fma_f32 v42, v50, v42, v98
	v_mul_f32_e32 v57, 0xbfb8aa3b, v43
	v_fma_f32 v36, v50, v36, v92
	v_fma_f32 v37, v50, v37, v93
	v_fma_f32 v38, v50, v38, v94
	v_fma_f32 v39, v50, v39, v95
	v_fma_f32 v32, v50, v32, v88
	v_fma_f32 v33, v50, v33, v89
	v_fma_f32 v34, v50, v34, v90
	v_fma_f32 v35, v50, v35, v91
	v_mul_f32_e32 v50, 0xbfb8aa3b, v44
	v_mul_f32_e32 v51, 0xbfb8aa3b, v45
	v_mul_f32_e32 v52, 0xbfb8aa3b, v46
	v_mul_f32_e32 v53, 0xbfb8aa3b, v47
	v_mul_f32_e32 v54, 0xbfb8aa3b, v40
	v_mul_f32_e32 v55, 0xbfb8aa3b, v41
	v_mul_f32_e32 v56, 0xbfb8aa3b, v42
	v_exp_f32_e32 v57, v57
	v_exp_f32_e32 v50, v50
	v_exp_f32_e32 v51, v51
	v_exp_f32_e32 v52, v52
	v_exp_f32_e32 v53, v53
	v_exp_f32_e32 v54, v54
	v_exp_f32_e32 v55, v55
	v_exp_f32_e32 v56, v56
	v_add_f32_e32 v57, 1.0, v57
	v_add_f32_e32 v50, 1.0, v50
	v_add_f32_e32 v51, 1.0, v51
	v_add_f32_e32 v52, 1.0, v52
	v_add_f32_e32 v53, 1.0, v53
	v_add_f32_e32 v54, 1.0, v54
	v_add_f32_e32 v55, 1.0, v55
	v_add_f32_e32 v56, 1.0, v56
	v_rcp_f32_e32 v57, v57
	v_rcp_f32_e32 v50, v50
	v_rcp_f32_e32 v51, v51
	v_rcp_f32_e32 v52, v52
	v_rcp_f32_e32 v53, v53
	v_rcp_f32_e32 v54, v54
	v_rcp_f32_e32 v55, v55
	v_rcp_f32_e32 v56, v56
	v_mul_f32_e32 v43, v43, v57
	v_mul_f32_e32 v44, v44, v50
	v_mul_f32_e32 v45, v45, v51
	v_mul_f32_e32 v46, v46, v52
	v_mul_f32_e32 v47, v47, v53
	v_mul_f32_e32 v40, v40, v54
	v_mul_f32_e32 v41, v41, v55
	v_mul_f32_e32 v42, v42, v56
	v_mul_f32_e32 v35, v35, v43
	v_mul_f32_e32 v36, v36, v44
	v_mul_f32_e32 v37, v37, v45
	v_mul_f32_e32 v38, v38, v46
	v_mul_f32_e32 v39, v39, v47
	v_mul_f32_e32 v40, v32, v40
	v_mul_f32_e32 v41, v33, v41
	v_mul_f32_e32 v42, v34, v42
	v_cvt_pk_bf16_f32 v32, v36, v37
	v_cvt_pk_bf16_f32 v33, v38, v39
	v_cvt_pk_bf16_f32 v34, v40, v41
	v_cvt_pk_bf16_f32 v35, v42, v35
	global_store_dwordx4 v[48:49], v[32:35], off
	s_nop 0
	s_nop 0
	v_add_u32_e32 v33, 0xa0, v162
	s_nop 0
	v_fmamk_f32 v32, v195, 0x3a000000, v174
	v_rsq_f32_e32 v34, v32
; __device__ __forceinline__ unsigned pk2(float lo, float hi) { unsigned r; asm volatile("v_cvt_pk_bf16_f32 %0, %1, %2" : "=v"(r) : "v"(lo), "v"(hi)); return r; }
; __device__ __forceinline__ float sigmoidf_(float x) { return frcp(1.0f + fexp2(-x * LOG2E)); }
;     __device__ __forceinline__ void operator()(const f32x4 (&acc)[2][2][4][2], const Unit& u, int wr, int wc, int fr, int fq) const {
;         const int row0 = u.pm * BM + wr * 64 + fr, col0 = u.pn * HALF + wc * 32 + 8 * fq; const float* cb = c2 + (size_t)(u.pm >> 4) * (2 * DFF) + col0;
;         const f32x4 cg[2] = {*(const f32x4*)cb, *(const f32x4*)(cb + 4)}, cu[2] = {*(const f32x4*)(cb + DFF), *(const f32x4*)(cb + DFF + 4)};
; #pragma unroll
;         for (int ai = 0; ai < 2; ++ai)
; #pragma unroll
;             for (int m = 0; m < 4; ++m) { bf16_t* rowp = O + (size_t)(row0 + ai * HALF + m * 16) * DFF + col0; float v[8];
;                 const float rs = __builtin_amdgcn_rsqf(rowss[row0 + ai * HALF + m * 16] * (1.0f / DM) + 1e-6f);
; #pragma unroll
;                 for (int n = 0; n < 2; ++n)
; #pragma unroll
;                     for (int j = 0; j < 4; ++j) { const float g = __builtin_fmaf(rs, acc[ai][0][m][n][j], cg[n][j]), up = __builtin_fmaf(rs, acc[ai][1][m][n][j], cu[n][j]); v[4 * n + j] = g * sigmoidf_(g) * up; }
;                 u32x4 w; w.x = pk2(v[0], v[1]); w.y = pk2(v[2], v[3]); w.z = pk2(v[4], v[5]); w.w = pk2(v[6], v[7]);
;                 *(u32x4*)rowp = w; }
	v_mad_i64_i32 v[32:33], s[24:25], v33, s46, v[164:165]
	v_lshl_add_u64 v[32:33], v[32:33], 0, v[168:169]
	v_fma_f32 v27, v34, v27, v99
	v_fma_f32 v28, v34, v28, v80
	v_fma_f32 v29, v34, v29, v81
	v_fma_f32 v30, v34, v30, v82
	v_fma_f32 v31, v34, v31, v83
	v_fma_f32 v24, v34, v24, v96
	v_fma_f32 v25, v34, v25, v97
	v_fma_f32 v26, v34, v26, v98
	v_mul_f32_e32 v41, 0xbfb8aa3b, v27
	v_fma_f32 v20, v34, v20, v92
	v_fma_f32 v21, v34, v21, v93
	v_fma_f32 v22, v34, v22, v94
	v_fma_f32 v23, v34, v23, v95
	v_fma_f32 v16, v34, v16, v88
	v_fma_f32 v17, v34, v17, v89
	v_fma_f32 v18, v34, v18, v90
	v_fma_f32 v19, v34, v19, v91
	v_mul_f32_e32 v34, 0xbfb8aa3b, v28
	v_mul_f32_e32 v35, 0xbfb8aa3b, v29
	v_mul_f32_e32 v36, 0xbfb8aa3b, v30
	v_mul_f32_e32 v37, 0xbfb8aa3b, v31
	v_mul_f32_e32 v38, 0xbfb8aa3b, v24
	v_mul_f32_e32 v39, 0xbfb8aa3b, v25
	v_mul_f32_e32 v40, 0xbfb8aa3b, v26
	v_exp_f32_e32 v41, v41
	v_exp_f32_e32 v34, v34
	v_exp_f32_e32 v35, v35
	v_exp_f32_e32 v36, v36
	v_exp_f32_e32 v37, v37
	v_exp_f32_e32 v38, v38
	v_exp_f32_e32 v39, v39
	v_exp_f32_e32 v40, v40
	v_add_f32_e32 v41, 1.0, v41
	v_add_f32_e32 v34, 1.0, v34
	v_add_f32_e32 v35, 1.0, v35
	v_add_f32_e32 v36, 1.0, v36
	v_add_f32_e32 v37, 1.0, v37
	v_add_f32_e32 v38, 1.0, v38
	v_add_f32_e32 v39, 1.0, v39
	v_add_f32_e32 v40, 1.0, v40
	v_rcp_f32_e32 v41, v41
	v_rcp_f32_e32 v34, v34
	v_rcp_f32_e32 v35, v35
	v_rcp_f32_e32 v36, v36
	v_rcp_f32_e32 v37, v37
	v_rcp_f32_e32 v38, v38
	v_rcp_f32_e32 v39, v39
	v_rcp_f32_e32 v40, v40
	v_mul_f32_e32 v27, v27, v41
	v_mul_f32_e32 v28, v28, v34
	v_mul_f32_e32 v29, v29, v35
	v_mul_f32_e32 v30, v30, v36
	v_mul_f32_e32 v31, v31, v37
	v_mul_f32_e32 v24, v24, v38
	v_mul_f32_e32 v25, v25, v39
	v_mul_f32_e32 v26, v26, v40
	v_mul_f32_e32 v19, v19, v27
	v_mul_f32_e32 v20, v20, v28
	v_mul_f32_e32 v21, v21, v29
	v_mul_f32_e32 v22, v22, v30
	v_mul_f32_e32 v23, v23, v31
	v_mul_f32_e32 v24, v16, v24
	v_mul_f32_e32 v25, v17, v25
	v_mul_f32_e32 v26, v18, v26
	v_cvt_pk_bf16_f32 v16, v20, v21
	v_cvt_pk_bf16_f32 v17, v22, v23
	v_cvt_pk_bf16_f32 v18, v24, v25
	v_cvt_pk_bf16_f32 v19, v26, v19
	global_store_dwordx4 v[32:33], v[16:19], off
	s_nop 0
	s_nop 0
	v_add_u32_e32 v17, 0xb0, v162
	s_nop 0
	v_fmamk_f32 v16, v196, 0x3a000000, v174
	v_rsq_f32_e32 v18, v16
	v_mad_i64_i32 v[16:17], s[24:25], v17, s46, v[164:165]
	v_lshl_add_u64 v[16:17], v[16:17], 0, v[168:169]
	v_fma_f32 v12, v18, v12, v80
	v_fma_f32 v13, v18, v13, v81
	v_fma_f32 v14, v18, v14, v82
	v_fmac_f32_e32 v83, v18, v15
	v_fmac_f32_e32 v95, v18, v7
	v_fma_f32 v7, v18, v8, v96
	v_fma_f32 v8, v18, v9, v97
	v_fma_f32 v9, v18, v10, v98
	v_fmac_f32_e32 v99, v18, v11
	v_fmac_f32_e32 v91, v18, v3
	v_mul_f32_e32 v3, 0xbfb8aa3b, v12
	v_fma_f32 v4, v18, v4, v92
	v_fma_f32 v5, v18, v5, v93
	v_fma_f32 v6, v18, v6, v94
	v_fma_f32 v0, v18, v0, v88
	v_fma_f32 v1, v18, v1, v89
	v_fma_f32 v2, v18, v2, v90
	v_mul_f32_e32 v10, 0xbfb8aa3b, v13
	v_mul_f32_e32 v11, 0xbfb8aa3b, v14
	v_mul_f32_e32 v15, 0xbfb8aa3b, v83
	v_mul_f32_e32 v18, 0xbfb8aa3b, v7
	v_mul_f32_e32 v19, 0xbfb8aa3b, v8
	v_mul_f32_e32 v20, 0xbfb8aa3b, v9
	v_mul_f32_e32 v21, 0xbfb8aa3b, v99
	v_exp_f32_e32 v3, v3
	v_exp_f32_e32 v10, v10
	v_exp_f32_e32 v11, v11
	v_exp_f32_e32 v15, v15
	v_exp_f32_e32 v18, v18
	v_exp_f32_e32 v19, v19
	v_exp_f32_e32 v20, v20
	v_exp_f32_e32 v21, v21
	v_add_f32_e32 v3, 1.0, v3
	v_add_f32_e32 v10, 1.0, v10
	v_add_f32_e32 v11, 1.0, v11
	v_add_f32_e32 v15, 1.0, v15
	v_add_f32_e32 v18, 1.0, v18
	v_add_f32_e32 v19, 1.0, v19
	v_add_f32_e32 v20, 1.0, v20
	v_add_f32_e32 v21, 1.0, v21
	v_rcp_f32_e32 v3, v3
	v_rcp_f32_e32 v10, v10
	v_rcp_f32_e32 v11, v11
	v_rcp_f32_e32 v15, v15
	v_rcp_f32_e32 v18, v18
	v_rcp_f32_e32 v19, v19
	v_rcp_f32_e32 v20, v20
	v_rcp_f32_e32 v21, v21
	v_mul_f32_e32 v3, v12, v3
	v_mul_f32_e32 v10, v13, v10
	v_mul_f32_e32 v11, v14, v11
	v_mul_f32_e32 v12, v83, v15
	v_mul_f32_e32 v7, v7, v18
	v_mul_f32_e32 v8, v8, v19
	v_mul_f32_e32 v9, v9, v20
	v_mul_f32_e32 v13, v99, v21
	v_mul_f32_e32 v3, v4, v3
	v_mul_f32_e32 v4, v5, v10
	v_mul_f32_e32 v5, v6, v11
	v_mul_f32_e32 v6, v95, v12
	v_mul_f32_e32 v7, v0, v7
	v_mul_f32_e32 v8, v1, v8
	v_mul_f32_e32 v9, v2, v9
	v_mul_f32_e32 v10, v91, v13
	v_cvt_pk_bf16_f32 v0, v3, v4
	v_cvt_pk_bf16_f32 v1, v5, v6
	v_cvt_pk_bf16_f32 v2, v7, v8
	v_cvt_pk_bf16_f32 v3, v9, v10
	global_store_dwordx4 v[16:17], v[0:3], off
	s_cbranch_vccnz .LBB0_1051
	s_andn2_b64 vcc, exec, s[6:7]
	s_cbranch_vccnz .LBB0_1050
	s_barrier
	s_branch .LBB0_1050
